# pb2 + trailing half-workgroup at s_setprio 1 during its epilogue (it is the one the next unit waits for)
# baseline (speedup 1.0000x reference)
.LBB0_325:
	s_setprio 1
	s_lshl_b32 s0, s89, 8
	v_add_u32_e32 v176, s0, v171
	v_ashrrev_i32_e32 v177, 31, v176
	v_or_b32_e32 v172, 16, v176
	v_lshlrev_b64 v[132:133], 6, v[176:177]
	v_ashrrev_i32_e32 v173, 31, v172
	v_or_b32_e32 v168, 32, v176
	v_lshl_add_u64 v[132:133], v[154:155], 0, v[132:133]
	v_lshlrev_b64 v[134:135], 6, v[172:173]
	v_ashrrev_i32_e32 v169, 31, v168
	v_lshl_add_u64 v[134:135], v[154:155], 0, v[134:135]
	global_load_dwordx4 v[180:183], v[132:133], off
	global_load_dwordx4 v[184:187], v[134:135], off
	v_lshlrev_b64 v[132:133], 6, v[168:169]
	v_lshl_add_u64 v[132:133], v[154:155], 0, v[132:133]
	global_load_dwordx4 v[188:191], v[132:133], off
	v_or_b32_e32 v166, 48, v176
	v_ashrrev_i32_e32 v167, 31, v166
	v_lshlrev_b64 v[132:133], 6, v[166:167]
	v_lshl_add_u64 v[132:133], v[154:155], 0, v[132:133]
	global_load_dwordx4 v[192:195], v[132:133], off
	v_add_u32_e32 v162, 0x80, v176
	v_ashrrev_i32_e32 v163, 31, v162
	v_lshlrev_b64 v[132:133], 6, v[162:163]
	v_lshl_add_u64 v[132:133], v[154:155], 0, v[132:133]
	global_load_dwordx4 v[204:207], v[132:133], off
	s_addk_i32 s0, 0xc000
	s_lshr_b32 s0, s0, 12
	v_add_u32_e32 v164, 0x90, v176
	s_ashr_i32 s1, s89, 5
	v_and_b32_e32 v132, 64, v229
	v_ashrrev_i32_e32 v165, 31, v164
	s_add_i32 s0, s0, 2
	v_add_u32_e32 v136, 64, v132
	v_lshlrev_b64 v[132:133], 6, v[164:165]
	v_add_u32_e32 v160, 0xa0, v176
	s_cmp_lt_i32 s89, 64
	v_lshl_add_u64 v[132:133], v[154:155], 0, v[132:133]
	v_ashrrev_i32_e32 v161, 31, v160
	s_cselect_b32 s0, s1, s0
	v_xor_b32_e32 v134, 16, v229
	global_load_dwordx4 v[208:211], v[132:133], off
	v_add_u32_e32 v158, 0xb0, v176
	v_lshlrev_b64 v[132:133], 6, v[160:161]
	s_mul_hi_i32 s1, s0, 0x1800
	s_mulk_i32 s0, 0x1800
	v_lshl_or_b32 v156, s90, 8, v178
	v_xor_b32_e32 v135, 32, v229
	v_cmp_lt_i32_e32 vcc, v134, v136
	v_ashrrev_i32_e32 v159, 31, v158
	v_lshl_add_u64 v[132:133], v[154:155], 0, v[132:133]
	s_add_u32 s0, s78, s0
	v_ashrrev_i32_e32 v157, 31, v156
	v_cndmask_b32_e32 v134, v229, v134, vcc
	v_cmp_lt_i32_e32 vcc, v135, v136
	global_load_dwordx4 v[212:215], v[132:133], off
	v_lshlrev_b64 v[132:133], 6, v[158:159]
	s_addc_u32 s1, s79, s1
	v_cndmask_b32_e32 v135, v229, v135, vcc
	v_lshl_add_u64 v[132:133], v[154:155], 0, v[132:133]
	v_lshl_add_u64 v[136:137], v[156:157], 2, s[0:1]
	v_lshlrev_b32_e32 v161, 2, v134
	v_lshlrev_b32_e32 v163, 2, v135
	global_load_dwordx4 v[216:219], v[132:133], off
	global_load_dwordx4 v[140:143], v[136:137], off offset:16
	global_load_dwordx4 v[144:147], v[136:137], off
	s_nop 0
	global_load_dwordx4 v[132:135], v[136:137], off offset:528
	s_nop 0
	global_load_dwordx4 v[136:139], v[136:137], off offset:512

.LBB0_867:
	s_setprio 1
	s_lshl_b32 s6, s94, 8
	s_add_i32 s5, s6, 0xffffc000
	s_lshr_b32 s5, s5, 12
	s_ashr_i32 s4, s94, 5
	s_add_i32 s5, s5, 2
	s_cmp_lt_i32 s94, 64
	s_cselect_b32 s4, s4, s5
	s_ashr_i32 s5, s4, 31
	s_lshl_b64 s[4:5], s[4:5], 14
	v_lshl_or_b32 v164, s18, 8, v240
	s_add_u32 s44, s79, s4
	s_addc_u32 s45, s88, s5
	v_ashrrev_i32_e32 v165, 31, v164
	v_add_u32_e32 v222, s6, v238
	s_add_u32 s4, s89, s4
	v_lshlrev_b64 v[210:211], 1, v[164:165]
	v_ashrrev_i32_e32 v223, 31, v222
	v_lshlrev_b64 v[90:91], 2, v[164:165]
	s_addc_u32 s5, s90, s5
	v_lshl_add_u64 v[164:165], s[82:83], 0, v[210:211]
	v_lshlrev_b64 v[226:227], 11, v[222:223]
	v_lshl_add_u64 v[92:93], s[44:45], 0, v[90:91]
	v_lshl_add_u64 v[94:95], s[4:5], 0, v[90:91]
	v_lshl_add_u64 v[166:167], v[164:165], 0, v[226:227]
	global_load_dwordx4 v[120:123], v[92:93], off offset:16
	global_load_dwordx4 v[128:131], v[92:93], off
	global_load_dwordx4 v[108:111], v[94:95], off offset:16
	global_load_dwordx4 v[112:115], v[94:95], off
	global_load_dwordx4 v[100:103], v[92:93], off offset:528
	global_load_dwordx4 v[104:107], v[92:93], off offset:512
	s_nop 0
	global_load_dwordx4 v[90:93], v[94:95], off offset:528
	s_nop 0
	global_load_dwordx4 v[94:97], v[94:95], off offset:512
	s_nop 0
	global_load_dwordx4 v[192:195], v[166:167], off
	global_load_dwordx4 v[188:191], v[166:167], off offset:256
	v_or_b32_e32 v220, 16, v222
	v_ashrrev_i32_e32 v221, 31, v220
	v_or_b32_e32 v216, 32, v222
	v_or_b32_e32 v212, 48, v222
	v_lshlrev_b64 v[224:225], 11, v[220:221]
	v_ashrrev_i32_e32 v217, 31, v216
	v_ashrrev_i32_e32 v213, 31, v212
	v_lshl_add_u64 v[166:167], v[164:165], 0, v[224:225]
	v_lshlrev_b64 v[218:219], 11, v[216:217]
	v_lshlrev_b64 v[214:215], 11, v[212:213]
	global_load_dwordx4 v[184:187], v[166:167], off
	global_load_dwordx4 v[180:183], v[166:167], off offset:256
	v_lshl_add_u64 v[166:167], v[164:165], 0, v[218:219]
	v_lshl_add_u64 v[164:165], v[164:165], 0, v[214:215]
	global_load_dwordx4 v[176:179], v[166:167], off
	global_load_dwordx4 v[172:175], v[166:167], off offset:256
	global_load_dwordx4 v[168:171], v[164:165], off
	s_nop 0
	global_load_dwordx4 v[164:167], v[164:165], off offset:256

.LBB0_911:
	s_setprio 1
	s_lshl_b32 s15, s92, 8
	s_add_i32 s5, s15, 0xffffc000
	s_lshr_b32 s5, s5, 12
	s_ashr_i32 s4, s92, 5
	s_add_i32 s5, s5, 2
	s_cmp_lt_i32 s92, 64
	v_add_u32_e32 v214, s15, v222
	v_readlane_b32 s56, v252, 3
	s_cselect_b32 s4, s4, s5
	v_add_u32_e32 v88, 0xffffc000, v214
	v_ashrrev_i32_e32 v215, 31, v214
	v_cmp_gt_i32_e32 vcc, s21, v214
	v_readlane_b32 s57, v252, 4
	v_readlane_b32 s58, v252, 5
	v_readlane_b32 s59, v252, 6
	v_lshl_or_b32 v212, s18, 8, v224
	s_ashr_i32 s5, s4, 31
	v_cndmask_b32_e32 v89, 0, v215, vcc
	v_cndmask_b32_e32 v88, v88, v214, vcc
	v_mov_b32_e32 v170, s59
	v_mov_b32_e32 v171, s57
	v_mov_b32_e32 v172, s58
	v_mov_b32_e32 v173, s56
	s_lshl_b64 s[4:5], s[4:5], 14
	v_ashrrev_i32_e32 v213, 31, v212
	v_cndmask_b32_e32 v91, v170, v171, vcc
	v_cndmask_b32_e32 v90, v172, v173, vcc
	v_lshlrev_b64 v[88:89], 12, v[88:89]
	s_add_u32 s44, s79, s4
	v_lshlrev_b64 v[164:165], 2, v[212:213]
	v_lshl_add_u64 v[88:89], v[90:91], 0, v[88:89]
	s_addc_u32 s45, s88, s5
	v_lshl_add_u64 v[166:167], v[88:89], 0, v[164:165]
	v_lshl_add_u64 v[86:87], s[44:45], 0, v[164:165]
	global_load_dwordx4 v[238:241], v[166:167], off
	global_load_dwordx4 v[124:127], v[86:87], off
	global_load_dwordx4 v[116:119], v[86:87], off offset:16
	global_load_dwordx4 v[242:245], v[166:167], off offset:16
	s_add_u32 s4, s89, s4
	s_addc_u32 s5, s90, s5
	v_lshl_add_u64 v[90:91], s[4:5], 0, v[164:165]
	global_load_dwordx4 v[112:115], v[90:91], off
	global_load_dwordx4 v[108:111], v[90:91], off offset:16
	global_load_dwordx4 v[100:103], v[86:87], off offset:528
	global_load_dwordx4 v[104:107], v[86:87], off offset:512
	s_nop 0
	global_load_dwordx4 v[86:89], v[90:91], off offset:528
	s_nop 0
	global_load_dwordx4 v[90:93], v[90:91], off offset:512
	s_nop 0
	global_load_dwordx4 v[246:249], v[166:167], off offset:528
	global_load_dwordx4 v[200:203], v[166:167], off offset:512
	v_or_b32_e32 v220, 16, v214
	v_ashrrev_i32_e32 v221, 31, v220
	v_add_u32_e32 v166, 0xffffc010, v214
	v_cmp_gt_i32_e32 vcc, s21, v220
	v_or_b32_e32 v216, 32, v214
	v_ashrrev_i32_e32 v217, 31, v216
	v_cndmask_b32_e32 v167, 0, v221, vcc
	v_cndmask_b32_e32 v166, v166, v220, vcc
	v_cndmask_b32_e32 v169, v170, v171, vcc
	v_cndmask_b32_e32 v168, v172, v173, vcc
	v_lshlrev_b64 v[166:167], 12, v[166:167]
	v_lshl_add_u64 v[166:167], v[168:169], 0, v[166:167]
	v_lshl_add_u64 v[166:167], v[166:167], 0, v[164:165]
	global_load_dwordx4 v[188:191], v[166:167], off offset:16
	global_load_dwordx4 v[192:195], v[166:167], off
	global_load_dwordx4 v[180:183], v[166:167], off offset:528
	global_load_dwordx4 v[184:187], v[166:167], off offset:512
	v_add_u32_e32 v166, 0xffffc020, v214
	v_cmp_gt_i32_e32 vcc, s21, v216
	v_and_b32_e32 v211, 64, v229
	v_xor_b32_e32 v210, 16, v229
	v_cndmask_b32_e32 v167, 0, v217, vcc
	v_cndmask_b32_e32 v166, v166, v216, vcc
	v_cndmask_b32_e32 v169, v170, v171, vcc
	v_cndmask_b32_e32 v168, v172, v173, vcc
	v_lshlrev_b64 v[166:167], 12, v[166:167]
	v_lshl_add_u64 v[166:167], v[168:169], 0, v[166:167]
	v_lshl_add_u64 v[168:169], v[166:167], 0, v[164:165]
	global_load_dwordx4 v[172:175], v[168:169], off offset:16
	global_load_dwordx4 v[176:179], v[168:169], off
	global_load_dwordx4 v[164:167], v[168:169], off offset:528
	s_nop 0
	global_load_dwordx4 v[168:171], v[168:169], off offset:512

.LBB0_1014:
	s_setprio 1
	s_lshl_b32 s4, s77, 8
	v_add_u32_e32 v162, s4, v188
	v_ashrrev_i32_e32 v163, 31, v162
	v_or_b32_e32 v180, 16, v162
	v_lshlrev_b64 v[132:133], 6, v[162:163]
	v_ashrrev_i32_e32 v181, 31, v180
	v_or_b32_e32 v176, 32, v162
	v_lshl_add_u64 v[132:133], v[154:155], 0, v[132:133]
	v_lshlrev_b64 v[134:135], 6, v[180:181]
	v_ashrrev_i32_e32 v177, 31, v176
	v_lshl_add_u64 v[134:135], v[154:155], 0, v[134:135]
	global_load_dwordx4 v[192:195], v[132:133], off
	global_load_dwordx4 v[200:203], v[134:135], off
	v_lshlrev_b64 v[132:133], 6, v[176:177]
	v_lshl_add_u64 v[132:133], v[154:155], 0, v[132:133]
	global_load_dwordx4 v[204:207], v[132:133], off
	v_or_b32_e32 v170, 48, v162
	v_ashrrev_i32_e32 v171, 31, v170
	v_lshlrev_b64 v[132:133], 6, v[170:171]
	v_lshl_add_u64 v[132:133], v[154:155], 0, v[132:133]
	global_load_dwordx4 v[208:211], v[132:133], off
	v_add_u32_e32 v166, 0x80, v162
	v_ashrrev_i32_e32 v167, 31, v166
	v_lshlrev_b64 v[132:133], 6, v[166:167]
	v_lshl_add_u64 v[132:133], v[154:155], 0, v[132:133]
	global_load_dwordx4 v[212:215], v[132:133], off
	v_add_u32_e32 v164, 0x90, v162
	v_and_b32_e32 v132, 64, v229
	v_ashrrev_i32_e32 v165, 31, v164
	v_add_u32_e32 v136, 64, v132
	v_lshlrev_b64 v[132:133], 6, v[164:165]
	v_lshl_add_u64 v[132:133], v[154:155], 0, v[132:133]
	global_load_dwordx4 v[216:219], v[132:133], off
	v_add_u32_e32 v158, 0xa0, v162
	v_ashrrev_i32_e32 v159, 31, v158
	v_add_u32_e32 v156, 0xb0, v162
	v_lshlrev_b64 v[132:133], 6, v[158:159]
	v_ashrrev_i32_e32 v157, 31, v156
	v_lshl_add_u64 v[132:133], v[154:155], 0, v[132:133]
	global_load_dwordx4 v[220:223], v[132:133], off
	v_lshlrev_b64 v[132:133], 6, v[156:157]
	v_lshl_add_u64 v[132:133], v[154:155], 0, v[132:133]
	global_load_dwordx4 v[224:227], v[132:133], off
	s_addk_i32 s4, 0xc000
	s_lshr_b32 s4, s4, 12
	s_ashr_i32 s5, s77, 5
	s_add_i32 s4, s4, 2
	s_cmp_lt_i32 s77, 64
	s_cselect_b32 s4, s5, s4
	s_ashr_i32 s5, s4, 31
	v_xor_b32_e32 v134, 16, v229
	s_lshl_b64 s[4:5], s[4:5], 14
	v_lshl_or_b32 v238, s79, 8, v190
	v_xor_b32_e32 v135, 32, v229
	v_cmp_lt_i32_e32 vcc, v134, v136
	s_add_u32 s4, s71, s4
	v_ashrrev_i32_e32 v239, 31, v238
	v_cndmask_b32_e32 v134, v229, v134, vcc
	v_cmp_lt_i32_e32 vcc, v135, v136
	s_addc_u32 s5, s74, s5
	v_lshl_add_u64 v[136:137], v[238:239], 2, s[4:5]
	v_cndmask_b32_e32 v135, v229, v135, vcc
	v_lshlrev_b32_e32 v160, 2, v134
	v_lshlrev_b32_e32 v168, 2, v135
	global_load_dwordx4 v[140:143], v[136:137], off offset:16
	global_load_dwordx4 v[144:147], v[136:137], off
	global_load_dwordx4 v[132:135], v[136:137], off offset:528
	s_nop 0
	global_load_dwordx4 v[136:139], v[136:137], off offset:512

.LBB0_1119:
	s_setprio 1
	s_lshl_b32 s4, s70, 8
	v_add_u32_e32 v194, s4, v204
	s_addk_i32 s4, 0xc000
	s_lshr_b32 s4, s4, 12
	s_ashr_i32 s5, s70, 5
	s_add_i32 s4, s4, 2
	s_cmp_lt_i32 s70, 64
	v_lshl_or_b32 v178, s20, 8, v206
	s_cselect_b32 s4, s5, s4
	v_ashrrev_i32_e32 v179, 31, v178
	s_ashr_i32 s5, s4, 31
	v_lshlrev_b64 v[180:181], 1, v[178:179]
	v_ashrrev_i32_e32 v195, 31, v194
	s_lshl_b64 s[4:5], s[4:5], 14
	v_lshl_add_u64 v[148:149], s[82:83], 0, v[180:181]
	v_lshlrev_b64 v[214:215], 11, v[194:195]
	s_add_u32 s4, s89, s4
	v_lshl_add_u64 v[112:113], v[148:149], 0, v[214:215]
	s_addc_u32 s5, s90, s5
	global_load_dwordx4 v[200:203], v[112:113], off
	global_load_dwordx4 v[210:213], v[112:113], off offset:256
	v_lshl_add_u64 v[112:113], v[178:179], 2, s[4:5]
	global_load_dwordx4 v[128:131], v[112:113], off
	global_load_dwordx4 v[124:127], v[112:113], off offset:16
	global_load_dwordx4 v[116:119], v[112:113], off offset:512
	s_nop 0
	global_load_dwordx4 v[112:115], v[112:113], off offset:528
	v_or_b32_e32 v190, 16, v194
	v_or_b32_e32 v186, 32, v194
	v_or_b32_e32 v182, 48, v194
	v_ashrrev_i32_e32 v191, 31, v190
	v_ashrrev_i32_e32 v187, 31, v186
	v_ashrrev_i32_e32 v183, 31, v182
	v_lshlrev_b64 v[192:193], 11, v[190:191]
	v_lshlrev_b64 v[188:189], 11, v[186:187]
	v_lshlrev_b64 v[184:185], 11, v[182:183]
	v_lshl_add_u64 v[150:151], v[148:149], 0, v[192:193]
	v_lshl_add_u64 v[152:153], v[148:149], 0, v[188:189]
	v_lshl_add_u64 v[148:149], v[148:149], 0, v[184:185]
	global_load_dwordx4 v[168:171], v[150:151], off
	global_load_dwordx4 v[164:167], v[150:151], off offset:256
	global_load_dwordx4 v[160:163], v[152:153], off
	global_load_dwordx4 v[156:159], v[152:153], off offset:256
	s_nop 0
	global_load_dwordx4 v[152:155], v[148:149], off
	s_nop 0
	global_load_dwordx4 v[148:151], v[148:149], off offset:256

.LBB0_1175:
	s_setprio 1
	s_lshl_b32 s6, s68, 8
	s_add_i32 s5, s6, 0xffffc000
	s_lshr_b32 s5, s5, 12
	s_ashr_i32 s4, s68, 5
	s_add_i32 s5, s5, 2
	s_cmp_lt_i32 s68, 64
	s_cselect_b32 s4, s4, s5
	s_ashr_i32 s5, s4, 31
	s_lshl_b64 s[4:5], s[4:5], 14
	v_lshl_or_b32 v164, s56, 8, v240
	s_add_u32 s44, s89, s4
	s_addc_u32 s45, s90, s5
	v_ashrrev_i32_e32 v165, 31, v164
	v_add_u32_e32 v222, s6, v238
	s_add_u32 s4, s8, s4
	v_lshlrev_b64 v[210:211], 1, v[164:165]
	v_ashrrev_i32_e32 v223, 31, v222
	v_lshlrev_b64 v[90:91], 2, v[164:165]
	s_addc_u32 s5, s9, s5
	v_lshl_add_u64 v[164:165], s[82:83], 0, v[210:211]
	v_lshlrev_b64 v[226:227], 11, v[222:223]
	v_lshl_add_u64 v[92:93], s[44:45], 0, v[90:91]
	v_lshl_add_u64 v[94:95], s[4:5], 0, v[90:91]
	v_lshl_add_u64 v[166:167], v[164:165], 0, v[226:227]
	global_load_dwordx4 v[120:123], v[92:93], off offset:16
	global_load_dwordx4 v[128:131], v[92:93], off
	global_load_dwordx4 v[108:111], v[94:95], off offset:16
	global_load_dwordx4 v[112:115], v[94:95], off
	global_load_dwordx4 v[100:103], v[92:93], off offset:528
	global_load_dwordx4 v[104:107], v[92:93], off offset:512
	s_nop 0
	global_load_dwordx4 v[90:93], v[94:95], off offset:528
	s_nop 0
	global_load_dwordx4 v[94:97], v[94:95], off offset:512
	s_nop 0
	global_load_dwordx4 v[192:195], v[166:167], off
	global_load_dwordx4 v[188:191], v[166:167], off offset:256
	v_or_b32_e32 v220, 16, v222
	v_ashrrev_i32_e32 v221, 31, v220
	v_or_b32_e32 v216, 32, v222
	v_or_b32_e32 v212, 48, v222
	v_lshlrev_b64 v[224:225], 11, v[220:221]
	v_ashrrev_i32_e32 v217, 31, v216
	v_ashrrev_i32_e32 v213, 31, v212
	v_lshl_add_u64 v[166:167], v[164:165], 0, v[224:225]
	v_lshlrev_b64 v[218:219], 11, v[216:217]
	v_lshlrev_b64 v[214:215], 11, v[212:213]
	global_load_dwordx4 v[184:187], v[166:167], off
	global_load_dwordx4 v[180:183], v[166:167], off offset:256
	v_lshl_add_u64 v[166:167], v[164:165], 0, v[218:219]
	v_lshl_add_u64 v[164:165], v[164:165], 0, v[214:215]
	global_load_dwordx4 v[176:179], v[166:167], off
	global_load_dwordx4 v[172:175], v[166:167], off offset:256
	global_load_dwordx4 v[168:171], v[164:165], off
	s_nop 0
	global_load_dwordx4 v[164:167], v[164:165], off offset:256
